# head-epilogue rope: dropped the second-block full drains that only waited for the first block's output stores (cos/sin already waited in the first block)
# speedup vs baseline: 1.0062x; 1.0062x over previous
.LBB0_264:
	v_pk_mul_f32 v[110:111], v[186:187], v[110:111]
	v_pk_mul_f32 v[112:113], v[134:135], v[112:113]
	v_pk_mul_f32 v[114:115], v[188:189], v[114:115]
	s_and_b64 vcc, exec, s[42:43]
	v_pk_mul_f32 v[116:117], v[136:137], v[116:117]
	s_cbranch_vccnz .LBB0_274
	v_mov_b32_e32 v96, v112
	v_mov_b32_e32 v97, v112
	v_mov_b32_e32 v99, v116
	v_mov_b32_e32 v100, v116
	v_mov_b32_e32 v101, v113
	v_mov_b32_e32 v118, v113
	v_mov_b32_e32 v119, v117
	v_mov_b32_e32 v120, v117
	v_mov_b32_e32 v121, v110
	v_mov_b32_e32 v122, v110
	v_mov_b32_e32 v123, v114
	v_mov_b32_e32 v124, v114
	v_mov_b32_e32 v125, v111
	v_mov_b32_e32 v127, v111
	v_mov_b32_e32 v126, v115
	v_mov_b32_e32 v191, v115
	v_permlane16_swap_b32_e32 v96, v97
	v_permlane16_swap_b32_e32 v99, v100
	v_permlane16_swap_b32_e32 v101, v118
	v_permlane16_swap_b32_e32 v119, v120
	v_permlane16_swap_b32_e32 v121, v122
	v_permlane16_swap_b32_e32 v123, v124
	v_permlane16_swap_b32_e32 v125, v127
	v_permlane16_swap_b32_e32 v126, v191
	v_cndmask_b32_e64 v98, v96, v97, s[44:45]
	v_cndmask_b32_e64 v96, v99, v100, s[44:45]
	v_cndmask_b32_e64 v99, v101, v118, s[44:45]
	v_cndmask_b32_e64 v97, v119, v120, s[44:45]
	v_cndmask_b32_e64 v120, v121, v122, s[44:45]
	v_cndmask_b32_e64 v118, v123, v124, s[44:45]
	v_cndmask_b32_e64 v121, v125, v127, s[44:45]
	v_cndmask_b32_e64 v119, v126, v191, s[44:45]
	v_cmp_lt_i32_e32 vcc, 0, v219
	s_and_saveexec_b64 s[2:3], vcc
	s_xor_b64 s[2:3], exec, s[2:3]
	s_cbranch_execz .LBB0_269
	v_cmp_eq_u32_e32 vcc, 1, v219
	s_and_saveexec_b64 s[4:5], vcc
	s_cbranch_execz .LBB0_268
	v_pk_mul_f32 v[98:99], v[146:147], v[98:99]
	v_pk_mul_f32 v[100:101], v[148:149], v[120:121]
	v_pk_fma_f32 v[112:113], v[150:151], v[112:113], v[98:99]
	v_pk_mul_f32 v[98:99], v[140:141], v[118:119]
	v_pk_mul_f32 v[96:97], v[138:139], v[96:97]
	v_pk_fma_f32 v[110:111], v[152:153], v[110:111], v[100:101]
	v_pk_fma_f32 v[114:115], v[144:145], v[114:115], v[98:99]
	v_pk_fma_f32 v[116:117], v[142:143], v[116:117], v[96:97]

.LBB0_269:
	s_andn2_saveexec_b64 s[2:3], s[2:3]
	s_cbranch_execz .LBB0_273
	v_cmp_eq_u32_e32 vcc, 0, v219
	s_and_saveexec_b64 s[4:5], vcc
	s_cbranch_execz .LBB0_272
	v_pk_mul_f32 v[98:99], v[146:147], v[98:99]
	v_pk_mul_f32 v[100:101], v[148:149], v[120:121]
	v_pk_fma_f32 v[112:113], v[150:151], v[112:113], v[98:99] neg_lo:[0,0,1] neg_hi:[0,0,1]
	v_pk_mul_f32 v[98:99], v[140:141], v[118:119]
	v_pk_mul_f32 v[96:97], v[138:139], v[96:97]
	v_pk_fma_f32 v[110:111], v[152:153], v[110:111], v[100:101] neg_lo:[0,0,1] neg_hi:[0,0,1]
	v_pk_fma_f32 v[114:115], v[144:145], v[114:115], v[98:99] neg_lo:[0,0,1] neg_hi:[0,0,1]
	v_pk_fma_f32 v[116:117], v[142:143], v[116:117], v[96:97] neg_lo:[0,0,1] neg_hi:[0,0,1]

.LBB0_290:
	v_pk_mul_f32 v[78:79], v[186:187], v[78:79]
	v_pk_mul_f32 v[80:81], v[134:135], v[80:81]
	v_pk_mul_f32 v[82:83], v[188:189], v[82:83]
	s_and_b64 vcc, exec, s[42:43]
	v_pk_mul_f32 v[84:85], v[136:137], v[84:85]
	s_cbranch_vccnz .LBB0_300
	v_mov_b32_e32 v64, v80
	v_mov_b32_e32 v65, v80
	v_mov_b32_e32 v67, v84
	v_mov_b32_e32 v68, v84
	v_mov_b32_e32 v69, v81
	v_mov_b32_e32 v86, v81
	v_mov_b32_e32 v87, v85
	v_mov_b32_e32 v88, v85
	v_mov_b32_e32 v89, v78
	v_mov_b32_e32 v90, v78
	v_mov_b32_e32 v91, v82
	v_mov_b32_e32 v92, v82
	v_mov_b32_e32 v93, v79
	v_mov_b32_e32 v95, v79
	v_mov_b32_e32 v94, v83
	v_mov_b32_e32 v96, v83
	v_permlane16_swap_b32_e32 v64, v65
	v_permlane16_swap_b32_e32 v67, v68
	v_permlane16_swap_b32_e32 v69, v86
	v_permlane16_swap_b32_e32 v87, v88
	v_permlane16_swap_b32_e32 v89, v90
	v_permlane16_swap_b32_e32 v91, v92
	v_permlane16_swap_b32_e32 v93, v95
	v_permlane16_swap_b32_e32 v94, v96
	v_cndmask_b32_e64 v66, v64, v65, s[44:45]
	v_cndmask_b32_e64 v64, v67, v68, s[44:45]
	v_cndmask_b32_e64 v67, v69, v86, s[44:45]
	v_cndmask_b32_e64 v65, v87, v88, s[44:45]
	v_cndmask_b32_e64 v88, v89, v90, s[44:45]
	v_cndmask_b32_e64 v86, v91, v92, s[44:45]
	v_cndmask_b32_e64 v89, v93, v95, s[44:45]
	v_cndmask_b32_e64 v87, v94, v96, s[44:45]
	v_cmp_lt_i32_e32 vcc, 0, v219
	s_and_saveexec_b64 s[2:3], vcc
	s_xor_b64 s[2:3], exec, s[2:3]
	s_cbranch_execz .LBB0_295
	v_cmp_eq_u32_e32 vcc, 1, v219
	s_and_saveexec_b64 s[4:5], vcc
	s_cbranch_execz .LBB0_294
	v_pk_mul_f32 v[66:67], v[146:147], v[66:67]
	v_pk_mul_f32 v[68:69], v[148:149], v[88:89]
	v_pk_fma_f32 v[80:81], v[150:151], v[80:81], v[66:67]
	v_pk_mul_f32 v[66:67], v[140:141], v[86:87]
	v_pk_mul_f32 v[64:65], v[138:139], v[64:65]
	v_pk_fma_f32 v[78:79], v[152:153], v[78:79], v[68:69]
	v_pk_fma_f32 v[82:83], v[144:145], v[82:83], v[66:67]
	v_pk_fma_f32 v[84:85], v[142:143], v[84:85], v[64:65]

.LBB0_295:
	s_andn2_saveexec_b64 s[2:3], s[2:3]
	s_cbranch_execz .LBB0_299
	v_cmp_eq_u32_e32 vcc, 0, v219
	s_and_saveexec_b64 s[4:5], vcc
	s_cbranch_execz .LBB0_298
	v_pk_mul_f32 v[66:67], v[146:147], v[66:67]
	v_pk_mul_f32 v[68:69], v[148:149], v[88:89]
	v_pk_fma_f32 v[80:81], v[150:151], v[80:81], v[66:67] neg_lo:[0,0,1] neg_hi:[0,0,1]
	v_pk_mul_f32 v[66:67], v[140:141], v[86:87]
	v_pk_mul_f32 v[64:65], v[138:139], v[64:65]
	v_pk_fma_f32 v[78:79], v[152:153], v[78:79], v[68:69] neg_lo:[0,0,1] neg_hi:[0,0,1]
	v_pk_fma_f32 v[82:83], v[144:145], v[82:83], v[66:67] neg_lo:[0,0,1] neg_hi:[0,0,1]
	v_pk_fma_f32 v[84:85], v[142:143], v[84:85], v[64:65] neg_lo:[0,0,1] neg_hi:[0,0,1]

.LBB0_316:
	v_pk_mul_f32 v[46:47], v[186:187], v[46:47]
	v_pk_mul_f32 v[48:49], v[134:135], v[48:49]
	v_pk_mul_f32 v[50:51], v[188:189], v[50:51]
	s_and_b64 vcc, exec, s[42:43]
	v_pk_mul_f32 v[52:53], v[136:137], v[52:53]
	s_cbranch_vccnz .LBB0_326
	v_mov_b32_e32 v32, v48
	v_mov_b32_e32 v33, v48
	v_mov_b32_e32 v35, v52
	v_mov_b32_e32 v36, v52
	v_mov_b32_e32 v37, v49
	v_mov_b32_e32 v54, v49
	v_mov_b32_e32 v55, v53
	v_mov_b32_e32 v56, v53
	v_mov_b32_e32 v57, v46
	v_mov_b32_e32 v58, v46
	v_mov_b32_e32 v59, v50
	v_mov_b32_e32 v60, v50
	v_mov_b32_e32 v61, v47
	v_mov_b32_e32 v63, v47
	v_mov_b32_e32 v62, v51
	v_mov_b32_e32 v65, v51
	v_permlane16_swap_b32_e32 v32, v33
	v_permlane16_swap_b32_e32 v35, v36
	v_permlane16_swap_b32_e32 v37, v54
	v_permlane16_swap_b32_e32 v55, v56
	v_permlane16_swap_b32_e32 v57, v58
	v_permlane16_swap_b32_e32 v59, v60
	v_permlane16_swap_b32_e32 v61, v63
	v_permlane16_swap_b32_e32 v62, v65
	v_cndmask_b32_e64 v34, v32, v33, s[44:45]
	v_cndmask_b32_e64 v32, v35, v36, s[44:45]
	v_cndmask_b32_e64 v35, v37, v54, s[44:45]
	v_cndmask_b32_e64 v33, v55, v56, s[44:45]
	v_cndmask_b32_e64 v56, v57, v58, s[44:45]
	v_cndmask_b32_e64 v54, v59, v60, s[44:45]
	v_cndmask_b32_e64 v57, v61, v63, s[44:45]
	v_cndmask_b32_e64 v55, v62, v65, s[44:45]
	v_cmp_lt_i32_e32 vcc, 0, v219
	s_and_saveexec_b64 s[2:3], vcc
	s_xor_b64 s[2:3], exec, s[2:3]
	s_cbranch_execz .LBB0_321
	v_cmp_eq_u32_e32 vcc, 1, v219
	s_and_saveexec_b64 s[4:5], vcc
	s_cbranch_execz .LBB0_320
	v_pk_mul_f32 v[34:35], v[146:147], v[34:35]
	v_pk_mul_f32 v[36:37], v[148:149], v[56:57]
	v_pk_fma_f32 v[48:49], v[150:151], v[48:49], v[34:35]
	v_pk_mul_f32 v[34:35], v[140:141], v[54:55]
	v_pk_mul_f32 v[32:33], v[138:139], v[32:33]
	v_pk_fma_f32 v[46:47], v[152:153], v[46:47], v[36:37]
	v_pk_fma_f32 v[50:51], v[144:145], v[50:51], v[34:35]
	v_pk_fma_f32 v[52:53], v[142:143], v[52:53], v[32:33]

.LBB0_321:
	s_andn2_saveexec_b64 s[2:3], s[2:3]
	s_cbranch_execz .LBB0_325
	v_cmp_eq_u32_e32 vcc, 0, v219
	s_and_saveexec_b64 s[4:5], vcc
	s_cbranch_execz .LBB0_324
	v_pk_mul_f32 v[34:35], v[146:147], v[34:35]
	v_pk_mul_f32 v[36:37], v[148:149], v[56:57]
	v_pk_fma_f32 v[48:49], v[150:151], v[48:49], v[34:35] neg_lo:[0,0,1] neg_hi:[0,0,1]
	v_pk_mul_f32 v[34:35], v[140:141], v[54:55]
	v_pk_mul_f32 v[32:33], v[138:139], v[32:33]
	v_pk_fma_f32 v[46:47], v[152:153], v[46:47], v[36:37] neg_lo:[0,0,1] neg_hi:[0,0,1]
	v_pk_fma_f32 v[50:51], v[144:145], v[50:51], v[34:35] neg_lo:[0,0,1] neg_hi:[0,0,1]
	v_pk_fma_f32 v[52:53], v[142:143], v[52:53], v[32:33] neg_lo:[0,0,1] neg_hi:[0,0,1]

.LBB0_342:
	v_pk_mul_f32 v[14:15], v[186:187], v[14:15]
	v_pk_mul_f32 v[16:17], v[134:135], v[16:17]
	v_pk_mul_f32 v[18:19], v[188:189], v[18:19]
	s_and_b64 vcc, exec, s[42:43]
	v_pk_mul_f32 v[20:21], v[136:137], v[20:21]
	s_cbranch_vccnz .LBB0_352
	v_mov_b32_e32 v0, v16
	v_mov_b32_e32 v1, v16
	v_mov_b32_e32 v3, v20
	v_mov_b32_e32 v4, v20
	v_mov_b32_e32 v5, v17
	v_mov_b32_e32 v22, v17
	v_mov_b32_e32 v23, v21
	v_mov_b32_e32 v24, v21
	v_mov_b32_e32 v25, v14
	v_mov_b32_e32 v26, v14
	v_mov_b32_e32 v27, v18
	v_mov_b32_e32 v28, v18
	v_mov_b32_e32 v29, v15
	v_mov_b32_e32 v31, v15
	v_mov_b32_e32 v30, v19
	v_mov_b32_e32 v32, v19
	v_permlane16_swap_b32_e32 v0, v1
	v_permlane16_swap_b32_e32 v3, v4
	v_permlane16_swap_b32_e32 v5, v22
	v_permlane16_swap_b32_e32 v23, v24
	v_permlane16_swap_b32_e32 v25, v26
	v_permlane16_swap_b32_e32 v27, v28
	v_permlane16_swap_b32_e32 v29, v31
	v_permlane16_swap_b32_e32 v30, v32
	v_cndmask_b32_e64 v2, v0, v1, s[44:45]
	v_cndmask_b32_e64 v0, v3, v4, s[44:45]
	v_cndmask_b32_e64 v3, v5, v22, s[44:45]
	v_cndmask_b32_e64 v1, v23, v24, s[44:45]
	v_cndmask_b32_e64 v24, v25, v26, s[44:45]
	v_cndmask_b32_e64 v22, v27, v28, s[44:45]
	v_cndmask_b32_e64 v25, v29, v31, s[44:45]
	v_cndmask_b32_e64 v23, v30, v32, s[44:45]
	v_cmp_lt_i32_e32 vcc, 0, v219
	s_and_saveexec_b64 s[2:3], vcc
	s_xor_b64 s[2:3], exec, s[2:3]
	s_cbranch_execz .LBB0_347
	v_cmp_eq_u32_e32 vcc, 1, v219
	s_and_saveexec_b64 s[4:5], vcc
	s_cbranch_execz .LBB0_346
	v_pk_mul_f32 v[2:3], v[146:147], v[2:3]
	v_pk_mul_f32 v[4:5], v[148:149], v[24:25]
	v_pk_fma_f32 v[16:17], v[150:151], v[16:17], v[2:3]
	v_pk_mul_f32 v[2:3], v[140:141], v[22:23]
	v_pk_mul_f32 v[0:1], v[138:139], v[0:1]
	v_pk_fma_f32 v[14:15], v[152:153], v[14:15], v[4:5]
	v_pk_fma_f32 v[18:19], v[144:145], v[18:19], v[2:3]
	v_pk_fma_f32 v[20:21], v[142:143], v[20:21], v[0:1]

.LBB0_347:
	s_andn2_saveexec_b64 s[2:3], s[2:3]
	s_cbranch_execz .LBB0_351
	v_cmp_eq_u32_e32 vcc, 0, v219
	s_and_saveexec_b64 s[4:5], vcc
	s_cbranch_execz .LBB0_350
	v_pk_mul_f32 v[2:3], v[146:147], v[2:3]
	v_pk_mul_f32 v[4:5], v[148:149], v[24:25]
	v_pk_fma_f32 v[16:17], v[150:151], v[16:17], v[2:3] neg_lo:[0,0,1] neg_hi:[0,0,1]
	v_pk_mul_f32 v[2:3], v[140:141], v[22:23]
	v_pk_mul_f32 v[0:1], v[138:139], v[0:1]
	v_pk_fma_f32 v[14:15], v[152:153], v[14:15], v[4:5] neg_lo:[0,0,1] neg_hi:[0,0,1]
	v_pk_fma_f32 v[18:19], v[144:145], v[18:19], v[2:3] neg_lo:[0,0,1] neg_hi:[0,0,1]
	v_pk_fma_f32 v[20:21], v[142:143], v[20:21], v[0:1] neg_lo:[0,0,1] neg_hi:[0,0,1]
